# f32 V-cache outputs written by the P1 C-tile epilogue (tiles of the V columns) instead of HBM-bound phase 2
# baseline (speedup 1.0000x reference)
.Lp1m_kloop:
	s_waitcnt vmcnt(0) lgkmcnt(0)
	s_barrier
	ds_read_b128 v[170:173], v232 offset:24576
	ds_read_b128 v[174:177], v232 offset:26624
	ds_read_b128 v[178:181], v230 offset:24576
	ds_read_b128 v[182:185], v230 offset:26624
	ds_read_b128 v[186:189], v230 offset:28672
	ds_read_b128 v[190:193], v230 offset:30720
	s_setprio 1
	v_mfma_f32_32x32x16_bf16 v[48:63], v[222:225], v[206:209], v[48:63]
	v_mfma_f32_32x32x16_bf16 v[32:47], v[222:225], v[210:213], v[32:47]
	v_mfma_f32_32x32x16_bf16 v[16:31], v[226:229], v[206:209], v[16:31]
	v_mfma_f32_32x32x16_bf16 v[0:15], v[226:229], v[210:213], v[0:15]
	s_setprio 0
	s_add_u32 m0, s101, 0xc000
	s_nop 0
	global_load_lds_dwordx4 v234, s[98:99]
	s_add_u32 m0, s101, 0x0
	s_nop 0
	global_load_lds_dwordx4 v234, s[44:45]
	s_add_u32 m0, s101, 0xc400
	s_nop 0
	global_load_lds_dwordx4 v235, s[98:99]
	s_add_u32 m0, s101, 0x400
	s_nop 0
	global_load_lds_dwordx4 v235, s[44:45]
	s_waitcnt lgkmcnt(2)
	s_setprio 1
	v_mfma_f32_32x32x16_bf16 v[112:127], v[178:181], v[170:173], v[112:127]
	v_mfma_f32_32x32x16_bf16 v[96:111], v[178:181], v[174:177], v[96:111]
	v_mfma_f32_32x32x16_bf16 v[80:95], v[182:185], v[170:173], v[80:95]
	v_mfma_f32_32x32x16_bf16 v[64:79], v[182:185], v[174:177], v[64:79]
	s_setprio 0
	ds_read_b128 v[206:209], v233 offset:24576
	ds_read_b128 v[210:213], v233 offset:26624
	ds_read_b128 v[214:217], v231 offset:24576
	ds_read_b128 v[218:221], v231 offset:26624
	s_add_u32 m0, s101, 0xc800
	s_nop 0
	global_load_lds_dwordx4 v236, s[98:99]
	s_add_u32 m0, s101, 0x800
	s_nop 0
	global_load_lds_dwordx4 v236, s[44:45]
	s_add_u32 m0, s101, 0xcc00
	s_nop 0
	global_load_lds_dwordx4 v237, s[98:99]
	s_add_u32 m0, s101, 0xc00
	s_nop 0
	global_load_lds_dwordx4 v237, s[44:45]
	s_waitcnt lgkmcnt(4)
	s_setprio 1
	v_mfma_f32_32x32x16_bf16 v[48:63], v[186:189], v[170:173], v[48:63]
	v_mfma_f32_32x32x16_bf16 v[32:47], v[186:189], v[174:177], v[32:47]
	v_mfma_f32_32x32x16_bf16 v[16:31], v[190:193], v[170:173], v[16:31]
	v_mfma_f32_32x32x16_bf16 v[0:15], v[190:193], v[174:177], v[0:15]
	s_setprio 0
	ds_read_b128 v[222:225], v231 offset:28672
	ds_read_b128 v[226:229], v231 offset:30720
	v_xad_u32 v241, s36, v240, v238
	v_xad_u32 v242, s37, v240, v239
	s_add_u32 m0, s49, 0xc000
	s_nop 0
	global_load_lds_dwordx4 v241, s[94:95]
	s_add_u32 m0, s49, 0xffffffc0
	s_nop 0
	global_load_lds_dwordx4 v241, s[94:95] offset:64
	s_add_u32 m0, s49, 0xc400
	s_nop 0
	global_load_lds_dwordx4 v242, s[94:95]
	s_add_u32 m0, s49, 0x3c0
	s_nop 0
	global_load_lds_dwordx4 v242, s[94:95] offset:64
	s_add_u32 s36, s36, 0x80
	s_xor_b32 s37, s36, 0x800
	s_add_u32 s98, s98, 128
	s_addc_u32 s99, s99, 0
	s_add_u32 s44, s44, 128
	s_addc_u32 s45, s45, 0
	s_waitcnt lgkmcnt(2)
	s_setprio 1
	v_mfma_f32_32x32x16_bf16 v[112:127], v[214:217], v[206:209], v[112:127]
	v_mfma_f32_32x32x16_bf16 v[96:111], v[214:217], v[210:213], v[96:111]
	v_mfma_f32_32x32x16_bf16 v[80:95], v[218:221], v[206:209], v[80:95]
	v_mfma_f32_32x32x16_bf16 v[64:79], v[218:221], v[210:213], v[64:79]
	s_setprio 0
	s_waitcnt vmcnt(0) lgkmcnt(0)
	s_barrier
	ds_read_b128 v[170:173], v232 offset:49152
	ds_read_b128 v[174:177], v232 offset:51200
	ds_read_b128 v[178:181], v230 offset:49152
	ds_read_b128 v[182:185], v230 offset:51200
	ds_read_b128 v[186:189], v230 offset:53248
	ds_read_b128 v[190:193], v230 offset:55296
	s_setprio 1
	v_mfma_f32_32x32x16_bf16 v[48:63], v[222:225], v[206:209], v[48:63]
	v_mfma_f32_32x32x16_bf16 v[32:47], v[222:225], v[210:213], v[32:47]
	v_mfma_f32_32x32x16_bf16 v[16:31], v[226:229], v[206:209], v[16:31]
	v_mfma_f32_32x32x16_bf16 v[0:15], v[226:229], v[210:213], v[0:15]
	s_setprio 0
	s_waitcnt lgkmcnt(2)
	s_setprio 1
	v_mfma_f32_32x32x16_bf16 v[112:127], v[178:181], v[170:173], v[112:127]
	v_mfma_f32_32x32x16_bf16 v[96:111], v[178:181], v[174:177], v[96:111]
	v_mfma_f32_32x32x16_bf16 v[80:95], v[182:185], v[170:173], v[80:95]
	v_mfma_f32_32x32x16_bf16 v[64:79], v[182:185], v[174:177], v[64:79]
	s_setprio 0
	ds_read_b128 v[206:209], v233 offset:49152
	ds_read_b128 v[210:213], v233 offset:51200
	ds_read_b128 v[214:217], v231 offset:49152
	ds_read_b128 v[218:221], v231 offset:51200
	s_waitcnt lgkmcnt(4)
	s_setprio 1
	v_mfma_f32_32x32x16_bf16 v[48:63], v[186:189], v[170:173], v[48:63]
	v_mfma_f32_32x32x16_bf16 v[32:47], v[186:189], v[174:177], v[32:47]
	v_mfma_f32_32x32x16_bf16 v[16:31], v[190:193], v[170:173], v[16:31]
	v_mfma_f32_32x32x16_bf16 v[0:15], v[190:193], v[174:177], v[0:15]
	s_setprio 0
	ds_read_b128 v[222:225], v231 offset:53248
	ds_read_b128 v[226:229], v231 offset:55296
	s_waitcnt lgkmcnt(2)
	s_setprio 1
	v_mfma_f32_32x32x16_bf16 v[112:127], v[214:217], v[206:209], v[112:127]
	v_mfma_f32_32x32x16_bf16 v[96:111], v[214:217], v[210:213], v[96:111]
	v_mfma_f32_32x32x16_bf16 v[80:95], v[218:221], v[206:209], v[80:95]
	v_mfma_f32_32x32x16_bf16 v[64:79], v[218:221], v[210:213], v[64:79]
	s_setprio 0
	s_waitcnt vmcnt(0) lgkmcnt(0)
	s_barrier
	ds_read_b128 v[170:173], v232 offset:0
	ds_read_b128 v[174:177], v232 offset:2048
	ds_read_b128 v[178:181], v230 offset:0
	ds_read_b128 v[182:185], v230 offset:2048
	ds_read_b128 v[186:189], v230 offset:4096
	ds_read_b128 v[190:193], v230 offset:6144
	s_setprio 1
	v_mfma_f32_32x32x16_bf16 v[48:63], v[222:225], v[206:209], v[48:63]
	v_mfma_f32_32x32x16_bf16 v[32:47], v[222:225], v[210:213], v[32:47]
	v_mfma_f32_32x32x16_bf16 v[16:31], v[226:229], v[206:209], v[16:31]
	v_mfma_f32_32x32x16_bf16 v[0:15], v[226:229], v[210:213], v[0:15]
	s_setprio 0
	s_add_u32 m0, s101, 0x6000
	s_nop 0
	global_load_lds_dwordx4 v234, s[98:99]
	s_add_u32 m0, s101, 0xc000
	s_nop 0
	global_load_lds_dwordx4 v234, s[44:45]
	s_add_u32 m0, s101, 0x6400
	s_nop 0
	global_load_lds_dwordx4 v235, s[98:99]
	s_add_u32 m0, s101, 0xc400
	s_nop 0
	global_load_lds_dwordx4 v235, s[44:45]
	s_waitcnt lgkmcnt(2)
	s_setprio 1
	v_mfma_f32_32x32x16_bf16 v[112:127], v[178:181], v[170:173], v[112:127]
	v_mfma_f32_32x32x16_bf16 v[96:111], v[178:181], v[174:177], v[96:111]
	v_mfma_f32_32x32x16_bf16 v[80:95], v[182:185], v[170:173], v[80:95]
	v_mfma_f32_32x32x16_bf16 v[64:79], v[182:185], v[174:177], v[64:79]
	s_setprio 0
	ds_read_b128 v[206:209], v233 offset:0
	ds_read_b128 v[210:213], v233 offset:2048
	ds_read_b128 v[214:217], v231 offset:0
	ds_read_b128 v[218:221], v231 offset:2048
	s_add_u32 m0, s101, 0x6800
	s_nop 0
	global_load_lds_dwordx4 v236, s[98:99]
	s_add_u32 m0, s101, 0xc800
	s_nop 0
	global_load_lds_dwordx4 v236, s[44:45]
	s_add_u32 m0, s101, 0x6c00
	s_nop 0
	global_load_lds_dwordx4 v237, s[98:99]
	s_add_u32 m0, s101, 0xcc00
	s_nop 0
	global_load_lds_dwordx4 v237, s[44:45]
	s_waitcnt lgkmcnt(4)
	s_setprio 1
	v_mfma_f32_32x32x16_bf16 v[48:63], v[186:189], v[170:173], v[48:63]
	v_mfma_f32_32x32x16_bf16 v[32:47], v[186:189], v[174:177], v[32:47]
	v_mfma_f32_32x32x16_bf16 v[16:31], v[190:193], v[170:173], v[16:31]
	v_mfma_f32_32x32x16_bf16 v[0:15], v[190:193], v[174:177], v[0:15]
	s_setprio 0
	ds_read_b128 v[222:225], v231 offset:4096
	ds_read_b128 v[226:229], v231 offset:6144
	v_xad_u32 v241, s36, v240, v238
	v_xad_u32 v242, s37, v240, v239
	s_add_u32 m0, s49, 0x6000
	s_nop 0
	global_load_lds_dwordx4 v241, s[94:95]
	s_add_u32 m0, s49, 0xbfc0
	s_nop 0
	global_load_lds_dwordx4 v241, s[94:95] offset:64
	s_add_u32 m0, s49, 0x6400
	s_nop 0
	global_load_lds_dwordx4 v242, s[94:95]
	s_add_u32 m0, s49, 0xc3c0
	s_nop 0
	global_load_lds_dwordx4 v242, s[94:95] offset:64
	s_add_u32 s36, s36, 0x80
	s_xor_b32 s37, s36, 0x800
	s_add_u32 s98, s98, 128
	s_addc_u32 s99, s99, 0
	s_add_u32 s44, s44, 128
	s_addc_u32 s45, s45, 0
	s_waitcnt lgkmcnt(2)
	s_setprio 1
	v_mfma_f32_32x32x16_bf16 v[112:127], v[214:217], v[206:209], v[112:127]
	v_mfma_f32_32x32x16_bf16 v[96:111], v[214:217], v[210:213], v[96:111]
	v_mfma_f32_32x32x16_bf16 v[80:95], v[218:221], v[206:209], v[80:95]
	v_mfma_f32_32x32x16_bf16 v[64:79], v[218:221], v[210:213], v[64:79]
	s_setprio 0
	s_waitcnt vmcnt(0) lgkmcnt(0)
	s_barrier
	ds_read_b128 v[170:173], v232 offset:24576
	ds_read_b128 v[174:177], v232 offset:26624
	ds_read_b128 v[178:181], v230 offset:24576
	ds_read_b128 v[182:185], v230 offset:26624
	ds_read_b128 v[186:189], v230 offset:28672
	ds_read_b128 v[190:193], v230 offset:30720
	s_setprio 1
	v_mfma_f32_32x32x16_bf16 v[48:63], v[222:225], v[206:209], v[48:63]
	v_mfma_f32_32x32x16_bf16 v[32:47], v[222:225], v[210:213], v[32:47]
	v_mfma_f32_32x32x16_bf16 v[16:31], v[226:229], v[206:209], v[16:31]
	v_mfma_f32_32x32x16_bf16 v[0:15], v[226:229], v[210:213], v[0:15]
	s_setprio 0
	s_waitcnt lgkmcnt(2)
	s_setprio 1
	v_mfma_f32_32x32x16_bf16 v[112:127], v[178:181], v[170:173], v[112:127]
	v_mfma_f32_32x32x16_bf16 v[96:111], v[178:181], v[174:177], v[96:111]
	v_mfma_f32_32x32x16_bf16 v[80:95], v[182:185], v[170:173], v[80:95]
	v_mfma_f32_32x32x16_bf16 v[64:79], v[182:185], v[174:177], v[64:79]
	s_setprio 0
	ds_read_b128 v[206:209], v233 offset:24576
	ds_read_b128 v[210:213], v233 offset:26624
	ds_read_b128 v[214:217], v231 offset:24576
	ds_read_b128 v[218:221], v231 offset:26624
	s_waitcnt lgkmcnt(4)
	s_setprio 1
	v_mfma_f32_32x32x16_bf16 v[48:63], v[186:189], v[170:173], v[48:63]
	v_mfma_f32_32x32x16_bf16 v[32:47], v[186:189], v[174:177], v[32:47]
	v_mfma_f32_32x32x16_bf16 v[16:31], v[190:193], v[170:173], v[16:31]
	v_mfma_f32_32x32x16_bf16 v[0:15], v[190:193], v[174:177], v[0:15]
	s_setprio 0
	ds_read_b128 v[222:225], v231 offset:28672
	ds_read_b128 v[226:229], v231 offset:30720
	s_waitcnt lgkmcnt(2)
	s_setprio 1
	v_mfma_f32_32x32x16_bf16 v[112:127], v[214:217], v[206:209], v[112:127]
	v_mfma_f32_32x32x16_bf16 v[96:111], v[214:217], v[210:213], v[96:111]
	v_mfma_f32_32x32x16_bf16 v[80:95], v[218:221], v[206:209], v[80:95]
	v_mfma_f32_32x32x16_bf16 v[64:79], v[218:221], v[210:213], v[64:79]
	s_setprio 0
	s_waitcnt vmcnt(0) lgkmcnt(0)
	s_barrier
	ds_read_b128 v[170:173], v232 offset:49152
	ds_read_b128 v[174:177], v232 offset:51200
	ds_read_b128 v[178:181], v230 offset:49152
	ds_read_b128 v[182:185], v230 offset:51200
	ds_read_b128 v[186:189], v230 offset:53248
	ds_read_b128 v[190:193], v230 offset:55296
	s_setprio 1
	v_mfma_f32_32x32x16_bf16 v[48:63], v[222:225], v[206:209], v[48:63]
	v_mfma_f32_32x32x16_bf16 v[32:47], v[222:225], v[210:213], v[32:47]
	v_mfma_f32_32x32x16_bf16 v[16:31], v[226:229], v[206:209], v[16:31]
	v_mfma_f32_32x32x16_bf16 v[0:15], v[226:229], v[210:213], v[0:15]
	s_setprio 0
	s_add_u32 m0, s101, 0x0
	s_nop 0
	global_load_lds_dwordx4 v234, s[98:99]
	s_add_u32 m0, s101, 0x6000
	s_nop 0
	global_load_lds_dwordx4 v234, s[44:45]
	s_add_u32 m0, s101, 0x400
	s_nop 0
	global_load_lds_dwordx4 v235, s[98:99]
	s_add_u32 m0, s101, 0x6400
	s_nop 0
	global_load_lds_dwordx4 v235, s[44:45]
	s_waitcnt lgkmcnt(2)
	s_setprio 1
	v_mfma_f32_32x32x16_bf16 v[112:127], v[178:181], v[170:173], v[112:127]
	v_mfma_f32_32x32x16_bf16 v[96:111], v[178:181], v[174:177], v[96:111]
	v_mfma_f32_32x32x16_bf16 v[80:95], v[182:185], v[170:173], v[80:95]
	v_mfma_f32_32x32x16_bf16 v[64:79], v[182:185], v[174:177], v[64:79]
	s_setprio 0
	ds_read_b128 v[206:209], v233 offset:49152
	ds_read_b128 v[210:213], v233 offset:51200
	ds_read_b128 v[214:217], v231 offset:49152
	ds_read_b128 v[218:221], v231 offset:51200
	s_add_u32 m0, s101, 0x800
	s_nop 0
	global_load_lds_dwordx4 v236, s[98:99]
	s_add_u32 m0, s101, 0x6800
	s_nop 0
	global_load_lds_dwordx4 v236, s[44:45]
	s_add_u32 m0, s101, 0xc00
	s_nop 0
	global_load_lds_dwordx4 v237, s[98:99]
	s_add_u32 m0, s101, 0x6c00
	s_nop 0
	global_load_lds_dwordx4 v237, s[44:45]
	s_waitcnt lgkmcnt(4)
	s_setprio 1
	v_mfma_f32_32x32x16_bf16 v[48:63], v[186:189], v[170:173], v[48:63]
	v_mfma_f32_32x32x16_bf16 v[32:47], v[186:189], v[174:177], v[32:47]
	v_mfma_f32_32x32x16_bf16 v[16:31], v[190:193], v[170:173], v[16:31]
	v_mfma_f32_32x32x16_bf16 v[0:15], v[190:193], v[174:177], v[0:15]
	s_setprio 0
	ds_read_b128 v[222:225], v231 offset:53248
	ds_read_b128 v[226:229], v231 offset:55296
	v_xad_u32 v241, s36, v240, v238
	v_xad_u32 v242, s37, v240, v239
	s_add_u32 m0, s49, 0x0
	s_nop 0
	global_load_lds_dwordx4 v241, s[94:95]
	s_add_u32 m0, s49, 0x5fc0
	s_nop 0
	global_load_lds_dwordx4 v241, s[94:95] offset:64
	s_add_u32 m0, s49, 0x400
	s_nop 0
	global_load_lds_dwordx4 v242, s[94:95]
	s_add_u32 m0, s49, 0x63c0
	s_nop 0
	global_load_lds_dwordx4 v242, s[94:95] offset:64
	s_add_u32 s36, s36, 0x80
	s_xor_b32 s37, s36, 0x800
	s_add_u32 s98, s98, 128
	s_addc_u32 s99, s99, 0
	s_add_u32 s44, s44, 128
	s_addc_u32 s45, s45, 0
	s_waitcnt lgkmcnt(2)
	s_setprio 1
	v_mfma_f32_32x32x16_bf16 v[112:127], v[214:217], v[206:209], v[112:127]
	v_mfma_f32_32x32x16_bf16 v[96:111], v[214:217], v[210:213], v[96:111]
	v_mfma_f32_32x32x16_bf16 v[80:95], v[218:221], v[206:209], v[80:95]
	v_mfma_f32_32x32x16_bf16 v[64:79], v[218:221], v[210:213], v[64:79]
	s_setprio 0
	s_waitcnt vmcnt(0) lgkmcnt(0)
	s_barrier
	ds_read_b128 v[170:173], v232 offset:0
	ds_read_b128 v[174:177], v232 offset:2048
	ds_read_b128 v[178:181], v230 offset:0
	ds_read_b128 v[182:185], v230 offset:2048
	ds_read_b128 v[186:189], v230 offset:4096
	ds_read_b128 v[190:193], v230 offset:6144
	s_setprio 1
	v_mfma_f32_32x32x16_bf16 v[48:63], v[222:225], v[206:209], v[48:63]
	v_mfma_f32_32x32x16_bf16 v[32:47], v[222:225], v[210:213], v[32:47]
	v_mfma_f32_32x32x16_bf16 v[16:31], v[226:229], v[206:209], v[16:31]
	v_mfma_f32_32x32x16_bf16 v[0:15], v[226:229], v[210:213], v[0:15]
	s_setprio 0
	s_waitcnt lgkmcnt(2)
	s_setprio 1
	v_mfma_f32_32x32x16_bf16 v[112:127], v[178:181], v[170:173], v[112:127]
	v_mfma_f32_32x32x16_bf16 v[96:111], v[178:181], v[174:177], v[96:111]
	v_mfma_f32_32x32x16_bf16 v[80:95], v[182:185], v[170:173], v[80:95]
	v_mfma_f32_32x32x16_bf16 v[64:79], v[182:185], v[174:177], v[64:79]
	s_setprio 0
	ds_read_b128 v[206:209], v233 offset:0
	ds_read_b128 v[210:213], v233 offset:2048
	ds_read_b128 v[214:217], v231 offset:0
	ds_read_b128 v[218:221], v231 offset:2048
	s_waitcnt lgkmcnt(4)
	s_setprio 1
	v_mfma_f32_32x32x16_bf16 v[48:63], v[186:189], v[170:173], v[48:63]
	v_mfma_f32_32x32x16_bf16 v[32:47], v[186:189], v[174:177], v[32:47]
	v_mfma_f32_32x32x16_bf16 v[16:31], v[190:193], v[170:173], v[16:31]
	v_mfma_f32_32x32x16_bf16 v[0:15], v[190:193], v[174:177], v[0:15]
	s_setprio 0
	ds_read_b128 v[222:225], v231 offset:4096
	ds_read_b128 v[226:229], v231 offset:6144
	s_waitcnt lgkmcnt(2)
	s_setprio 1
	v_mfma_f32_32x32x16_bf16 v[112:127], v[214:217], v[206:209], v[112:127]
	v_mfma_f32_32x32x16_bf16 v[96:111], v[214:217], v[210:213], v[96:111]
	v_mfma_f32_32x32x16_bf16 v[80:95], v[218:221], v[206:209], v[80:95]
	v_mfma_f32_32x32x16_bf16 v[64:79], v[218:221], v[210:213], v[64:79]
	s_setprio 0
	s_sub_u32 s100, s100, 1
	s_cmp_lg_u32 s100, 0
	s_cbranch_scc1 .Lp1m_kloop
	s_waitcnt vmcnt(0) lgkmcnt(0)
	s_barrier
	ds_read_b128 v[170:173], v232 offset:24576
	ds_read_b128 v[174:177], v232 offset:26624
	ds_read_b128 v[178:181], v230 offset:24576
	ds_read_b128 v[182:185], v230 offset:26624
	ds_read_b128 v[186:189], v230 offset:28672
	ds_read_b128 v[190:193], v230 offset:30720
	s_setprio 1
	v_mfma_f32_32x32x16_bf16 v[48:63], v[222:225], v[206:209], v[48:63]
	v_mfma_f32_32x32x16_bf16 v[32:47], v[222:225], v[210:213], v[32:47]
	v_mfma_f32_32x32x16_bf16 v[16:31], v[226:229], v[206:209], v[16:31]
	v_mfma_f32_32x32x16_bf16 v[0:15], v[226:229], v[210:213], v[0:15]
	s_setprio 0
	s_add_u32 m0, s101, 0xc000
	s_nop 0
	global_load_lds_dwordx4 v234, s[98:99]
	s_add_u32 m0, s101, 0x0
	s_nop 0
	global_load_lds_dwordx4 v234, s[44:45]
	s_add_u32 m0, s101, 0xc400
	s_nop 0
	global_load_lds_dwordx4 v235, s[98:99]
	s_add_u32 m0, s101, 0x400
	s_nop 0
	global_load_lds_dwordx4 v235, s[44:45]
	s_waitcnt lgkmcnt(2)
	s_setprio 1
	v_mfma_f32_32x32x16_bf16 v[112:127], v[178:181], v[170:173], v[112:127]
	v_mfma_f32_32x32x16_bf16 v[96:111], v[178:181], v[174:177], v[96:111]
	v_mfma_f32_32x32x16_bf16 v[80:95], v[182:185], v[170:173], v[80:95]
	v_mfma_f32_32x32x16_bf16 v[64:79], v[182:185], v[174:177], v[64:79]
	s_setprio 0
	ds_read_b128 v[206:209], v233 offset:24576
	ds_read_b128 v[210:213], v233 offset:26624
	ds_read_b128 v[214:217], v231 offset:24576
	ds_read_b128 v[218:221], v231 offset:26624
	s_add_u32 m0, s101, 0xc800
	s_nop 0
	global_load_lds_dwordx4 v236, s[98:99]
	s_add_u32 m0, s101, 0x800
	s_nop 0
	global_load_lds_dwordx4 v236, s[44:45]
	s_add_u32 m0, s101, 0xcc00
	s_nop 0
	global_load_lds_dwordx4 v237, s[98:99]
	s_add_u32 m0, s101, 0xc00
	s_nop 0
	global_load_lds_dwordx4 v237, s[44:45]
	s_waitcnt lgkmcnt(4)
	s_setprio 1
	v_mfma_f32_32x32x16_bf16 v[48:63], v[186:189], v[170:173], v[48:63]
	v_mfma_f32_32x32x16_bf16 v[32:47], v[186:189], v[174:177], v[32:47]
	v_mfma_f32_32x32x16_bf16 v[16:31], v[190:193], v[170:173], v[16:31]
	v_mfma_f32_32x32x16_bf16 v[0:15], v[190:193], v[174:177], v[0:15]
	s_setprio 0
	ds_read_b128 v[222:225], v231 offset:28672
	ds_read_b128 v[226:229], v231 offset:30720
	v_xad_u32 v241, s36, v240, v238
	v_xad_u32 v242, s37, v240, v239
	s_add_u32 m0, s49, 0xc000
	s_nop 0
	global_load_lds_dwordx4 v241, s[94:95]
	s_add_u32 m0, s49, 0xffffffc0
	s_nop 0
	global_load_lds_dwordx4 v241, s[94:95] offset:64
	s_add_u32 m0, s49, 0xc400
	s_nop 0
	global_load_lds_dwordx4 v242, s[94:95]
	s_add_u32 m0, s49, 0x3c0
	s_nop 0
	global_load_lds_dwordx4 v242, s[94:95] offset:64
	s_add_u32 s36, s36, 0x80
	s_xor_b32 s37, s36, 0x800
	s_add_u32 s98, s98, 128
	s_addc_u32 s99, s99, 0
	s_add_u32 s44, s44, 128
	s_addc_u32 s45, s45, 0
	s_waitcnt lgkmcnt(2)
	s_setprio 1
	v_mfma_f32_32x32x16_bf16 v[112:127], v[214:217], v[206:209], v[112:127]
	v_mfma_f32_32x32x16_bf16 v[96:111], v[214:217], v[210:213], v[96:111]
	v_mfma_f32_32x32x16_bf16 v[80:95], v[218:221], v[206:209], v[80:95]
	v_mfma_f32_32x32x16_bf16 v[64:79], v[218:221], v[210:213], v[64:79]
	s_setprio 0
	s_waitcnt vmcnt(0) lgkmcnt(0)
	s_barrier
	ds_read_b128 v[170:173], v232 offset:49152
	ds_read_b128 v[174:177], v232 offset:51200
	ds_read_b128 v[178:181], v230 offset:49152
	ds_read_b128 v[182:185], v230 offset:51200
	ds_read_b128 v[186:189], v230 offset:53248
	ds_read_b128 v[190:193], v230 offset:55296
	s_setprio 1
	v_mfma_f32_32x32x16_bf16 v[48:63], v[222:225], v[206:209], v[48:63]
	v_mfma_f32_32x32x16_bf16 v[32:47], v[222:225], v[210:213], v[32:47]
	v_mfma_f32_32x32x16_bf16 v[16:31], v[226:229], v[206:209], v[16:31]
	v_mfma_f32_32x32x16_bf16 v[0:15], v[226:229], v[210:213], v[0:15]
	s_setprio 0
	s_waitcnt lgkmcnt(2)
	s_setprio 1
	v_mfma_f32_32x32x16_bf16 v[112:127], v[178:181], v[170:173], v[112:127]
	v_mfma_f32_32x32x16_bf16 v[96:111], v[178:181], v[174:177], v[96:111]
	v_mfma_f32_32x32x16_bf16 v[80:95], v[182:185], v[170:173], v[80:95]
	v_mfma_f32_32x32x16_bf16 v[64:79], v[182:185], v[174:177], v[64:79]
	s_setprio 0
	ds_read_b128 v[206:209], v233 offset:49152
	ds_read_b128 v[210:213], v233 offset:51200
	ds_read_b128 v[214:217], v231 offset:49152
	ds_read_b128 v[218:221], v231 offset:51200
	s_waitcnt lgkmcnt(4)
	s_setprio 1
	v_mfma_f32_32x32x16_bf16 v[48:63], v[186:189], v[170:173], v[48:63]
	v_mfma_f32_32x32x16_bf16 v[32:47], v[186:189], v[174:177], v[32:47]
	v_mfma_f32_32x32x16_bf16 v[16:31], v[190:193], v[170:173], v[16:31]
	v_mfma_f32_32x32x16_bf16 v[0:15], v[190:193], v[174:177], v[0:15]
	s_setprio 0
	ds_read_b128 v[222:225], v231 offset:53248
	ds_read_b128 v[226:229], v231 offset:55296
	s_waitcnt lgkmcnt(2)
	s_setprio 1
	v_mfma_f32_32x32x16_bf16 v[112:127], v[214:217], v[206:209], v[112:127]
	v_mfma_f32_32x32x16_bf16 v[96:111], v[214:217], v[210:213], v[96:111]
	v_mfma_f32_32x32x16_bf16 v[80:95], v[218:221], v[206:209], v[80:95]
	v_mfma_f32_32x32x16_bf16 v[64:79], v[218:221], v[210:213], v[64:79]
	s_setprio 0
	s_waitcnt vmcnt(0) lgkmcnt(0)
	s_barrier
	ds_read_b128 v[170:173], v232 offset:0
	ds_read_b128 v[174:177], v232 offset:2048
	ds_read_b128 v[178:181], v230 offset:0
	ds_read_b128 v[182:185], v230 offset:2048
	ds_read_b128 v[186:189], v230 offset:4096
	ds_read_b128 v[190:193], v230 offset:6144
	s_setprio 1
	v_mfma_f32_32x32x16_bf16 v[48:63], v[222:225], v[206:209], v[48:63]
	v_mfma_f32_32x32x16_bf16 v[32:47], v[222:225], v[210:213], v[32:47]
	v_mfma_f32_32x32x16_bf16 v[16:31], v[226:229], v[206:209], v[16:31]
	v_mfma_f32_32x32x16_bf16 v[0:15], v[226:229], v[210:213], v[0:15]
	s_setprio 0
	s_waitcnt lgkmcnt(2)
	s_setprio 1
	v_mfma_f32_32x32x16_bf16 v[112:127], v[178:181], v[170:173], v[112:127]
	v_mfma_f32_32x32x16_bf16 v[96:111], v[178:181], v[174:177], v[96:111]
	v_mfma_f32_32x32x16_bf16 v[80:95], v[182:185], v[170:173], v[80:95]
	v_mfma_f32_32x32x16_bf16 v[64:79], v[182:185], v[174:177], v[64:79]
	s_setprio 0
	ds_read_b128 v[206:209], v233 offset:0
	ds_read_b128 v[210:213], v233 offset:2048
	ds_read_b128 v[214:217], v231 offset:0
	ds_read_b128 v[218:221], v231 offset:2048
	s_waitcnt lgkmcnt(4)
	s_setprio 1
	v_mfma_f32_32x32x16_bf16 v[48:63], v[186:189], v[170:173], v[48:63]
	v_mfma_f32_32x32x16_bf16 v[32:47], v[186:189], v[174:177], v[32:47]
	v_mfma_f32_32x32x16_bf16 v[16:31], v[190:193], v[170:173], v[16:31]
	v_mfma_f32_32x32x16_bf16 v[0:15], v[190:193], v[174:177], v[0:15]
	s_setprio 0
	ds_read_b128 v[222:225], v231 offset:4096
	ds_read_b128 v[226:229], v231 offset:6144
	s_waitcnt lgkmcnt(2)
	s_setprio 1
	v_mfma_f32_32x32x16_bf16 v[112:127], v[214:217], v[206:209], v[112:127]
	v_mfma_f32_32x32x16_bf16 v[96:111], v[214:217], v[210:213], v[96:111]
	v_mfma_f32_32x32x16_bf16 v[80:95], v[218:221], v[206:209], v[80:95]
	v_mfma_f32_32x32x16_bf16 v[64:79], v[218:221], v[210:213], v[64:79]
	s_setprio 0
	s_waitcnt lgkmcnt(0)
	s_setprio 1
	v_mfma_f32_32x32x16_bf16 v[48:63], v[222:225], v[206:209], v[48:63]
	v_mfma_f32_32x32x16_bf16 v[32:47], v[222:225], v[210:213], v[32:47]
	v_mfma_f32_32x32x16_bf16 v[16:31], v[226:229], v[206:209], v[16:31]
	v_mfma_f32_32x32x16_bf16 v[0:15], v[226:229], v[210:213], v[0:15]
	s_setprio 0
	s_mov_b32 s38, s40
	s_mov_b32 s39, s42
	s_mul_hi_i32 s41, s42, 0x540000
	s_mul_i32 s42, s42, 0x540000
	s_add_u32 s42, s31, s42
	s_addc_u32 s43, s33, s41
	s_lshl_b32 s40, s40, 8
	s_add_u32 s42, s42, s40
	s_addc_u32 s43, s43, 0
	s_add_i32 s16, s16, s17
	s_add_i32 s47, s47, s17
	v_lshrrev_b32_e32 v170, 6, v204
	v_and_b32_e32 v171, 31, v204
	v_bfe_u32 v172, v204, 5, 1
	v_mul_u32_u24_e32 v173, 0x4400, v170
	v_mul_u32_u24_e32 v174, 544, v172
	v_lshl_add_u32 v174, v171, 2, v174
	v_add3_u32 v174, v174, v173, 32
	v_and_b32_e32 v175, 7, v204
	v_bfe_u32 v176, v204, 3, 3
	v_mul_u32_u24_e32 v177, 272, v176
	v_lshl_add_u32 v177, v175, 5, v177
	v_add3_u32 v177, v177, v173, 32
	v_lshrrev_b32_e32 v178, 1, v170
	v_and_b32_e32 v179, 1, v170
	v_lshlrev_b32_e32 v178, 7, v178
	v_lshl_add_u32 v178, v176, 1, v178
	v_mul_u32_u24_e32 v178, 0x5400, v178
	v_lshl_add_u32 v178, v179, 7, v178
	v_lshl_add_u32 v178, v175, 4, v178
	v_add_u32_e32 v179, 0x5400, v178
	v_mov_b32_e32 v180, 0x05040100
	v_mov_b32_e32 v181, 0x07060302
	s_sub_u32 s37, s38, 16
	s_cmp_lt_u32 s37, 8
	s_cselect_b32 s36, 1, 0
	s_lshl_b32 s98, s39, 20
	s_add_u32 s99, s98, 0x6a00000
	s_add_u32 s98, s98, 0x6400000
	s_cmp_lt_u32 s39, 32
	s_cselect_b32 s98, s98, s99
	s_lshl_b32 s99, s37, 9
	s_add_u32 s98, s98, s99
	s_add_u32 s96, s92, s98
	s_addc_u32 s97, s93, 0
	v_lshrrev_b32_e32 v210, 1, v170
	v_lshlrev_b32_e32 v210, 7, v210
	v_lshl_add_u32 v210, v176, 1, v210
	v_lshlrev_b32_e32 v210, 12, v210
	v_and_b32_e32 v211, 1, v170
	v_lshl_add_u32 v210, v211, 8, v210
	v_lshl_add_u32 v210, v175, 5, v210
	v_add_u32_e32 v211, 0x1000, v210
	s_waitcnt vmcnt(0)
	s_barrier
	v_cvt_pk_bf16_f32 v112, v112, v113
	ds_write_b32 v174, v112 offset:0
	v_cvt_pk_bf16_f32 v114, v114, v115
	ds_write_b32 v174, v114 offset:272
	v_cvt_pk_bf16_f32 v116, v116, v117
	ds_write_b32 v174, v116 offset:1088
	v_cvt_pk_bf16_f32 v118, v118, v119
	ds_write_b32 v174, v118 offset:1360
	v_cvt_pk_bf16_f32 v120, v120, v121
	ds_write_b32 v174, v120 offset:2176
	v_cvt_pk_bf16_f32 v122, v122, v123
	ds_write_b32 v174, v122 offset:2448
	v_cvt_pk_bf16_f32 v124, v124, v125
	ds_write_b32 v174, v124 offset:3264
	v_cvt_pk_bf16_f32 v126, v126, v127
	ds_write_b32 v174, v126 offset:3536
	v_cvt_pk_bf16_f32 v96, v96, v97
	ds_write_b32 v174, v96 offset:128
	v_cvt_pk_bf16_f32 v98, v98, v99
	ds_write_b32 v174, v98 offset:400
	v_cvt_pk_bf16_f32 v100, v100, v101
	ds_write_b32 v174, v100 offset:1216
	v_cvt_pk_bf16_f32 v102, v102, v103
	ds_write_b32 v174, v102 offset:1488
	v_cvt_pk_bf16_f32 v104, v104, v105
	ds_write_b32 v174, v104 offset:2304
	v_cvt_pk_bf16_f32 v106, v106, v107
	ds_write_b32 v174, v106 offset:2576
	v_cvt_pk_bf16_f32 v108, v108, v109
	ds_write_b32 v174, v108 offset:3392
	v_cvt_pk_bf16_f32 v110, v110, v111
	ds_write_b32 v174, v110 offset:3664
	v_cvt_pk_bf16_f32 v80, v80, v81
	ds_write_b32 v174, v80 offset:4352
	v_cvt_pk_bf16_f32 v82, v82, v83
	ds_write_b32 v174, v82 offset:4624
	v_cvt_pk_bf16_f32 v84, v84, v85
	ds_write_b32 v174, v84 offset:5440
	v_cvt_pk_bf16_f32 v86, v86, v87
	ds_write_b32 v174, v86 offset:5712
	v_cvt_pk_bf16_f32 v88, v88, v89
	ds_write_b32 v174, v88 offset:6528
	v_cvt_pk_bf16_f32 v90, v90, v91
	ds_write_b32 v174, v90 offset:6800
	v_cvt_pk_bf16_f32 v92, v92, v93
	ds_write_b32 v174, v92 offset:7616
	v_cvt_pk_bf16_f32 v94, v94, v95
	ds_write_b32 v174, v94 offset:7888
	v_cvt_pk_bf16_f32 v64, v64, v65
	ds_write_b32 v174, v64 offset:4480
	v_cvt_pk_bf16_f32 v66, v66, v67
	ds_write_b32 v174, v66 offset:4752
	v_cvt_pk_bf16_f32 v68, v68, v69
	ds_write_b32 v174, v68 offset:5568
	v_cvt_pk_bf16_f32 v70, v70, v71
	ds_write_b32 v174, v70 offset:5840
	v_cvt_pk_bf16_f32 v72, v72, v73
	ds_write_b32 v174, v72 offset:6656
	v_cvt_pk_bf16_f32 v74, v74, v75
	ds_write_b32 v174, v74 offset:6928
	v_cvt_pk_bf16_f32 v76, v76, v77
	ds_write_b32 v174, v76 offset:7744
	v_cvt_pk_bf16_f32 v78, v78, v79
	ds_write_b32 v174, v78 offset:8016
	v_cvt_pk_bf16_f32 v48, v48, v49
	ds_write_b32 v174, v48 offset:8704
	v_cvt_pk_bf16_f32 v50, v50, v51
	ds_write_b32 v174, v50 offset:8976
	v_cvt_pk_bf16_f32 v52, v52, v53
	ds_write_b32 v174, v52 offset:9792
	v_cvt_pk_bf16_f32 v54, v54, v55
	ds_write_b32 v174, v54 offset:10064
	v_cvt_pk_bf16_f32 v56, v56, v57
	ds_write_b32 v174, v56 offset:10880
	v_cvt_pk_bf16_f32 v58, v58, v59
	ds_write_b32 v174, v58 offset:11152
	v_cvt_pk_bf16_f32 v60, v60, v61
	ds_write_b32 v174, v60 offset:11968
	v_cvt_pk_bf16_f32 v62, v62, v63
	ds_write_b32 v174, v62 offset:12240
	v_cvt_pk_bf16_f32 v32, v32, v33
	ds_write_b32 v174, v32 offset:8832
	v_cvt_pk_bf16_f32 v34, v34, v35
	ds_write_b32 v174, v34 offset:9104
	v_cvt_pk_bf16_f32 v36, v36, v37
	ds_write_b32 v174, v36 offset:9920
	v_cvt_pk_bf16_f32 v38, v38, v39
	ds_write_b32 v174, v38 offset:10192
	v_cvt_pk_bf16_f32 v40, v40, v41
	ds_write_b32 v174, v40 offset:11008
	v_cvt_pk_bf16_f32 v42, v42, v43
	ds_write_b32 v174, v42 offset:11280
	v_cvt_pk_bf16_f32 v44, v44, v45
	ds_write_b32 v174, v44 offset:12096
	v_cvt_pk_bf16_f32 v46, v46, v47
	ds_write_b32 v174, v46 offset:12368
	v_cvt_pk_bf16_f32 v16, v16, v17
	ds_write_b32 v174, v16 offset:13056
	v_cvt_pk_bf16_f32 v18, v18, v19
	ds_write_b32 v174, v18 offset:13328
	v_cvt_pk_bf16_f32 v20, v20, v21
	ds_write_b32 v174, v20 offset:14144
	v_cvt_pk_bf16_f32 v22, v22, v23
	ds_write_b32 v174, v22 offset:14416
	v_cvt_pk_bf16_f32 v24, v24, v25
	ds_write_b32 v174, v24 offset:15232
	v_cvt_pk_bf16_f32 v26, v26, v27
	ds_write_b32 v174, v26 offset:15504
	v_cvt_pk_bf16_f32 v28, v28, v29
	ds_write_b32 v174, v28 offset:16320
	v_cvt_pk_bf16_f32 v30, v30, v31
	ds_write_b32 v174, v30 offset:16592
	v_cvt_pk_bf16_f32 v0, v0, v1
	ds_write_b32 v174, v0 offset:13184
	v_cvt_pk_bf16_f32 v2, v2, v3
	ds_write_b32 v174, v2 offset:13456
	v_cvt_pk_bf16_f32 v4, v4, v5
	ds_write_b32 v174, v4 offset:14272
	v_cvt_pk_bf16_f32 v6, v6, v7
	ds_write_b32 v174, v6 offset:14544
	v_cvt_pk_bf16_f32 v8, v8, v9
	ds_write_b32 v174, v8 offset:15360
	v_cvt_pk_bf16_f32 v10, v10, v11
	ds_write_b32 v174, v10 offset:15632
	v_cvt_pk_bf16_f32 v12, v12, v13
	ds_write_b32 v174, v12 offset:16448
	v_cvt_pk_bf16_f32 v14, v14, v15
	ds_write_b32 v174, v14 offset:16720
	s_cmp_ge_i32 s16, s22
	s_cselect_b64 s[40:41], -1, 0
	s_waitcnt lgkmcnt(0)
	ds_read_b128 v[182:185], v177 offset:0
	ds_read_b128 v[186:189], v177 offset:16
	ds_read_b128 v[190:193], v177 offset:2176
	ds_read_b128 v[194:197], v177 offset:2192
	s_waitcnt lgkmcnt(2)
	v_perm_b32 v198, v183, v182, v180
	v_perm_b32 v199, v185, v184, v180
	v_perm_b32 v200, v187, v186, v180
	v_perm_b32 v201, v189, v188, v180
	v_perm_b32 v206, v183, v182, v181
	v_perm_b32 v207, v185, v184, v181
	v_perm_b32 v208, v187, v186, v181
	v_perm_b32 v209, v189, v188, v181
	global_store_dwordx4 v178, v[198:201], s[42:43]
	global_store_dwordx4 v179, v[206:209], s[42:43]
	s_cmp_eq_u32 s36, 1
	s_cbranch_scc0 .Lp1v_skip0
	v_lshlrev_b32_e32 v212, 16, v198
	v_and_b32_e32 v213, 0xffff0000, v198
	v_lshlrev_b32_e32 v220, 16, v206
	v_and_b32_e32 v221, 0xffff0000, v206
	v_lshlrev_b32_e32 v214, 16, v199
	v_and_b32_e32 v215, 0xffff0000, v199
	v_lshlrev_b32_e32 v222, 16, v207
	v_and_b32_e32 v223, 0xffff0000, v207
	v_lshlrev_b32_e32 v216, 16, v200
	v_and_b32_e32 v217, 0xffff0000, v200
	v_lshlrev_b32_e32 v224, 16, v208
	v_and_b32_e32 v225, 0xffff0000, v208
	v_lshlrev_b32_e32 v218, 16, v201
	v_and_b32_e32 v219, 0xffff0000, v201
	v_lshlrev_b32_e32 v226, 16, v209
	v_and_b32_e32 v227, 0xffff0000, v209
	global_store_dwordx4 v210, v[212:215], s[96:97]
	global_store_dwordx4 v210, v[216:219], s[96:97] offset:16
	global_store_dwordx4 v211, v[220:223], s[96:97]
	global_store_dwordx4 v211, v[224:227], s[96:97] offset:16
	s_add_u32 s96, s96, 0x10000
	s_addc_u32 s97, s97, 0
.Lp1v_skip0:
	s_add_u32 s42, s42, 0x54000
	s_addc_u32 s43, s43, 0
	s_nop 1
	ds_read_b128 v[182:185], v177 offset:4352
	ds_read_b128 v[186:189], v177 offset:4368
	s_waitcnt lgkmcnt(2)
	v_perm_b32 v198, v191, v190, v180
	v_perm_b32 v199, v193, v192, v180
	v_perm_b32 v200, v195, v194, v180
	v_perm_b32 v201, v197, v196, v180
	v_perm_b32 v206, v191, v190, v181
	v_perm_b32 v207, v193, v192, v181
	v_perm_b32 v208, v195, v194, v181
	v_perm_b32 v209, v197, v196, v181
	global_store_dwordx4 v178, v[198:201], s[42:43]
	global_store_dwordx4 v179, v[206:209], s[42:43]
	s_cmp_eq_u32 s36, 1
	s_cbranch_scc0 .Lp1v_skip1
	v_lshlrev_b32_e32 v212, 16, v198
	v_and_b32_e32 v213, 0xffff0000, v198
	v_lshlrev_b32_e32 v220, 16, v206
	v_and_b32_e32 v221, 0xffff0000, v206
	v_lshlrev_b32_e32 v214, 16, v199
	v_and_b32_e32 v215, 0xffff0000, v199
	v_lshlrev_b32_e32 v222, 16, v207
	v_and_b32_e32 v223, 0xffff0000, v207
	v_lshlrev_b32_e32 v216, 16, v200
	v_and_b32_e32 v217, 0xffff0000, v200
	v_lshlrev_b32_e32 v224, 16, v208
	v_and_b32_e32 v225, 0xffff0000, v208
	v_lshlrev_b32_e32 v218, 16, v201
	v_and_b32_e32 v219, 0xffff0000, v201
	v_lshlrev_b32_e32 v226, 16, v209
	v_and_b32_e32 v227, 0xffff0000, v209
	global_store_dwordx4 v210, v[212:215], s[96:97]
	global_store_dwordx4 v210, v[216:219], s[96:97] offset:16
	global_store_dwordx4 v211, v[220:223], s[96:97]
	global_store_dwordx4 v211, v[224:227], s[96:97] offset:16
	s_add_u32 s96, s96, 0x10000
	s_addc_u32 s97, s97, 0
.Lp1v_skip1:
	s_add_u32 s42, s42, 0x54000
	s_addc_u32 s43, s43, 0
	s_nop 1
	ds_read_b128 v[190:193], v177 offset:6528
	ds_read_b128 v[194:197], v177 offset:6544
	s_waitcnt lgkmcnt(2)
	v_perm_b32 v198, v183, v182, v180
	v_perm_b32 v199, v185, v184, v180
	v_perm_b32 v200, v187, v186, v180
	v_perm_b32 v201, v189, v188, v180
	v_perm_b32 v206, v183, v182, v181
	v_perm_b32 v207, v185, v184, v181
	v_perm_b32 v208, v187, v186, v181
	v_perm_b32 v209, v189, v188, v181
	global_store_dwordx4 v178, v[198:201], s[42:43]
	global_store_dwordx4 v179, v[206:209], s[42:43]
	s_cmp_eq_u32 s36, 1
	s_cbranch_scc0 .Lp1v_skip2
	v_lshlrev_b32_e32 v212, 16, v198
	v_and_b32_e32 v213, 0xffff0000, v198
	v_lshlrev_b32_e32 v220, 16, v206
	v_and_b32_e32 v221, 0xffff0000, v206
	v_lshlrev_b32_e32 v214, 16, v199
	v_and_b32_e32 v215, 0xffff0000, v199
	v_lshlrev_b32_e32 v222, 16, v207
	v_and_b32_e32 v223, 0xffff0000, v207
	v_lshlrev_b32_e32 v216, 16, v200
	v_and_b32_e32 v217, 0xffff0000, v200
	v_lshlrev_b32_e32 v224, 16, v208
	v_and_b32_e32 v225, 0xffff0000, v208
	v_lshlrev_b32_e32 v218, 16, v201
	v_and_b32_e32 v219, 0xffff0000, v201
	v_lshlrev_b32_e32 v226, 16, v209
	v_and_b32_e32 v227, 0xffff0000, v209
	global_store_dwordx4 v210, v[212:215], s[96:97]
	global_store_dwordx4 v210, v[216:219], s[96:97] offset:16
	global_store_dwordx4 v211, v[220:223], s[96:97]
	global_store_dwordx4 v211, v[224:227], s[96:97] offset:16
	s_add_u32 s96, s96, 0x10000
	s_addc_u32 s97, s97, 0
.Lp1v_skip2:
	s_add_u32 s42, s42, 0x54000
	s_addc_u32 s43, s43, 0
	s_nop 1
	ds_read_b128 v[182:185], v177 offset:8704
	ds_read_b128 v[186:189], v177 offset:8720
	s_waitcnt lgkmcnt(2)
	v_perm_b32 v198, v191, v190, v180
	v_perm_b32 v199, v193, v192, v180
	v_perm_b32 v200, v195, v194, v180
	v_perm_b32 v201, v197, v196, v180
	v_perm_b32 v206, v191, v190, v181
	v_perm_b32 v207, v193, v192, v181
	v_perm_b32 v208, v195, v194, v181
	v_perm_b32 v209, v197, v196, v181
	global_store_dwordx4 v178, v[198:201], s[42:43]
	global_store_dwordx4 v179, v[206:209], s[42:43]
	s_cmp_eq_u32 s36, 1
	s_cbranch_scc0 .Lp1v_skip3
	v_lshlrev_b32_e32 v212, 16, v198
	v_and_b32_e32 v213, 0xffff0000, v198
	v_lshlrev_b32_e32 v220, 16, v206
	v_and_b32_e32 v221, 0xffff0000, v206
	v_lshlrev_b32_e32 v214, 16, v199
	v_and_b32_e32 v215, 0xffff0000, v199
	v_lshlrev_b32_e32 v222, 16, v207
	v_and_b32_e32 v223, 0xffff0000, v207
	v_lshlrev_b32_e32 v216, 16, v200
	v_and_b32_e32 v217, 0xffff0000, v200
	v_lshlrev_b32_e32 v224, 16, v208
	v_and_b32_e32 v225, 0xffff0000, v208
	v_lshlrev_b32_e32 v218, 16, v201
	v_and_b32_e32 v219, 0xffff0000, v201
	v_lshlrev_b32_e32 v226, 16, v209
	v_and_b32_e32 v227, 0xffff0000, v209
	global_store_dwordx4 v210, v[212:215], s[96:97]
	global_store_dwordx4 v210, v[216:219], s[96:97] offset:16
	global_store_dwordx4 v211, v[220:223], s[96:97]
	global_store_dwordx4 v211, v[224:227], s[96:97] offset:16
	s_add_u32 s96, s96, 0x10000
	s_addc_u32 s97, s97, 0
.Lp1v_skip3:
	s_add_u32 s42, s42, 0x54000
	s_addc_u32 s43, s43, 0
	s_nop 1
	ds_read_b128 v[190:193], v177 offset:10880
	ds_read_b128 v[194:197], v177 offset:10896
	s_waitcnt lgkmcnt(2)
	v_perm_b32 v198, v183, v182, v180
	v_perm_b32 v199, v185, v184, v180
	v_perm_b32 v200, v187, v186, v180
	v_perm_b32 v201, v189, v188, v180
	v_perm_b32 v206, v183, v182, v181
	v_perm_b32 v207, v185, v184, v181
	v_perm_b32 v208, v187, v186, v181
	v_perm_b32 v209, v189, v188, v181
	global_store_dwordx4 v178, v[198:201], s[42:43]
	global_store_dwordx4 v179, v[206:209], s[42:43]
	s_cmp_eq_u32 s36, 1
	s_cbranch_scc0 .Lp1v_skip4
	v_lshlrev_b32_e32 v212, 16, v198
	v_and_b32_e32 v213, 0xffff0000, v198
	v_lshlrev_b32_e32 v220, 16, v206
	v_and_b32_e32 v221, 0xffff0000, v206
	v_lshlrev_b32_e32 v214, 16, v199
	v_and_b32_e32 v215, 0xffff0000, v199
	v_lshlrev_b32_e32 v222, 16, v207
	v_and_b32_e32 v223, 0xffff0000, v207
	v_lshlrev_b32_e32 v216, 16, v200
	v_and_b32_e32 v217, 0xffff0000, v200
	v_lshlrev_b32_e32 v224, 16, v208
	v_and_b32_e32 v225, 0xffff0000, v208
	v_lshlrev_b32_e32 v218, 16, v201
	v_and_b32_e32 v219, 0xffff0000, v201
	v_lshlrev_b32_e32 v226, 16, v209
	v_and_b32_e32 v227, 0xffff0000, v209
	global_store_dwordx4 v210, v[212:215], s[96:97]
	global_store_dwordx4 v210, v[216:219], s[96:97] offset:16
	global_store_dwordx4 v211, v[220:223], s[96:97]
	global_store_dwordx4 v211, v[224:227], s[96:97] offset:16
	s_add_u32 s96, s96, 0x10000
	s_addc_u32 s97, s97, 0
.Lp1v_skip4:
	s_add_u32 s42, s42, 0x54000
	s_addc_u32 s43, s43, 0
	s_nop 1
	ds_read_b128 v[182:185], v177 offset:13056
	ds_read_b128 v[186:189], v177 offset:13072
	s_waitcnt lgkmcnt(2)
	v_perm_b32 v198, v191, v190, v180
	v_perm_b32 v199, v193, v192, v180
	v_perm_b32 v200, v195, v194, v180
	v_perm_b32 v201, v197, v196, v180
	v_perm_b32 v206, v191, v190, v181
	v_perm_b32 v207, v193, v192, v181
	v_perm_b32 v208, v195, v194, v181
	v_perm_b32 v209, v197, v196, v181
	global_store_dwordx4 v178, v[198:201], s[42:43]
	global_store_dwordx4 v179, v[206:209], s[42:43]
	s_cmp_eq_u32 s36, 1
	s_cbranch_scc0 .Lp1v_skip5
	v_lshlrev_b32_e32 v212, 16, v198
	v_and_b32_e32 v213, 0xffff0000, v198
	v_lshlrev_b32_e32 v220, 16, v206
	v_and_b32_e32 v221, 0xffff0000, v206
	v_lshlrev_b32_e32 v214, 16, v199
	v_and_b32_e32 v215, 0xffff0000, v199
	v_lshlrev_b32_e32 v222, 16, v207
	v_and_b32_e32 v223, 0xffff0000, v207
	v_lshlrev_b32_e32 v216, 16, v200
	v_and_b32_e32 v217, 0xffff0000, v200
	v_lshlrev_b32_e32 v224, 16, v208
	v_and_b32_e32 v225, 0xffff0000, v208
	v_lshlrev_b32_e32 v218, 16, v201
	v_and_b32_e32 v219, 0xffff0000, v201
	v_lshlrev_b32_e32 v226, 16, v209
	v_and_b32_e32 v227, 0xffff0000, v209
	global_store_dwordx4 v210, v[212:215], s[96:97]
	global_store_dwordx4 v210, v[216:219], s[96:97] offset:16
	global_store_dwordx4 v211, v[220:223], s[96:97]
	global_store_dwordx4 v211, v[224:227], s[96:97] offset:16
	s_add_u32 s96, s96, 0x10000
	s_addc_u32 s97, s97, 0
.Lp1v_skip5:
	s_add_u32 s42, s42, 0x54000
	s_addc_u32 s43, s43, 0
	s_nop 1
	ds_read_b128 v[190:193], v177 offset:15232
	ds_read_b128 v[194:197], v177 offset:15248
	s_waitcnt lgkmcnt(2)
	v_perm_b32 v198, v183, v182, v180
	v_perm_b32 v199, v185, v184, v180
	v_perm_b32 v200, v187, v186, v180
	v_perm_b32 v201, v189, v188, v180
	v_perm_b32 v206, v183, v182, v181
	v_perm_b32 v207, v185, v184, v181
	v_perm_b32 v208, v187, v186, v181
	v_perm_b32 v209, v189, v188, v181
	global_store_dwordx4 v178, v[198:201], s[42:43]
	global_store_dwordx4 v179, v[206:209], s[42:43]
	s_cmp_eq_u32 s36, 1
	s_cbranch_scc0 .Lp1v_skip6
	v_lshlrev_b32_e32 v212, 16, v198
	v_and_b32_e32 v213, 0xffff0000, v198
	v_lshlrev_b32_e32 v220, 16, v206
	v_and_b32_e32 v221, 0xffff0000, v206
	v_lshlrev_b32_e32 v214, 16, v199
	v_and_b32_e32 v215, 0xffff0000, v199
	v_lshlrev_b32_e32 v222, 16, v207
	v_and_b32_e32 v223, 0xffff0000, v207
	v_lshlrev_b32_e32 v216, 16, v200
	v_and_b32_e32 v217, 0xffff0000, v200
	v_lshlrev_b32_e32 v224, 16, v208
	v_and_b32_e32 v225, 0xffff0000, v208
	v_lshlrev_b32_e32 v218, 16, v201
	v_and_b32_e32 v219, 0xffff0000, v201
	v_lshlrev_b32_e32 v226, 16, v209
	v_and_b32_e32 v227, 0xffff0000, v209
	global_store_dwordx4 v210, v[212:215], s[96:97]
	global_store_dwordx4 v210, v[216:219], s[96:97] offset:16
	global_store_dwordx4 v211, v[220:223], s[96:97]
	global_store_dwordx4 v211, v[224:227], s[96:97] offset:16
	s_add_u32 s96, s96, 0x10000
	s_addc_u32 s97, s97, 0
.Lp1v_skip6:
	s_add_u32 s42, s42, 0x54000
	s_addc_u32 s43, s43, 0
	s_nop 1
	s_waitcnt lgkmcnt(0)
	s_barrier
	v_perm_b32 v198, v191, v190, v180
	v_perm_b32 v199, v193, v192, v180
	v_perm_b32 v200, v195, v194, v180
	v_perm_b32 v201, v197, v196, v180
	v_perm_b32 v206, v191, v190, v181
	v_perm_b32 v207, v193, v192, v181
	v_perm_b32 v208, v195, v194, v181
	v_perm_b32 v209, v197, v196, v181
	global_store_dwordx4 v178, v[198:201], s[42:43]
	global_store_dwordx4 v179, v[206:209], s[42:43]
	s_cmp_eq_u32 s36, 1
	s_cbranch_scc0 .Lp1v_skip7
	v_lshlrev_b32_e32 v212, 16, v198
	v_and_b32_e32 v213, 0xffff0000, v198
	v_lshlrev_b32_e32 v220, 16, v206
	v_and_b32_e32 v221, 0xffff0000, v206
	v_lshlrev_b32_e32 v214, 16, v199
	v_and_b32_e32 v215, 0xffff0000, v199
	v_lshlrev_b32_e32 v222, 16, v207
	v_and_b32_e32 v223, 0xffff0000, v207
	v_lshlrev_b32_e32 v216, 16, v200
	v_and_b32_e32 v217, 0xffff0000, v200
	v_lshlrev_b32_e32 v224, 16, v208
	v_and_b32_e32 v225, 0xffff0000, v208
	v_lshlrev_b32_e32 v218, 16, v201
	v_and_b32_e32 v219, 0xffff0000, v201
	v_lshlrev_b32_e32 v226, 16, v209
	v_and_b32_e32 v227, 0xffff0000, v209
	global_store_dwordx4 v210, v[212:215], s[96:97]
	global_store_dwordx4 v210, v[216:219], s[96:97] offset:16
	global_store_dwordx4 v211, v[220:223], s[96:97]
	global_store_dwordx4 v211, v[224:227], s[96:97] offset:16
	s_add_u32 s96, s96, 0x10000
	s_addc_u32 s97, s97, 0
.Lp1v_skip7:
	s_branch .LBB0_126
.LBB0_131:
	s_not_b32 s6, s2
	s_add_i32 s16, s3, s6
	s_cmp_gt_i32 s16, 31
	s_cbranch_scc1 .LBB0_136
	s_add_u32 s17, s94, 0x19a88000
	s_addc_u32 s22, s95, 0
	s_add_u32 s23, s94, 0x17e88000
	s_addc_u32 s28, s95, 0
	s_add_u32 s29, s94, 0x1c108000
	s_addc_u32 s30, s95, 0
	s_xor_b32 s6, s2, 7
	s_add_i32 s31, s6, s3
	s_mov_b64 s[6:7], 0x10000
	s_mov_b64 s[8:9], 0x10040
	s_mov_b64 s[10:11], 0x19a98080
	s_mov_b64 s[12:13], 0x19aa8080
	s_mov_b64 s[14:15], 0x19ab8080
	s_mov_b64 s[18:19], 0x17e88080
	s_mov_b64 s[20:21], 0x17e98080
	s_mov_b64 s[24:25], 0x19a880c0
	s_mov_b64 s[26:27], 0x19a980c0
	s_mov_b64 s[34:35], 0x19aa80c0
	s_mov_b64 s[40:41], 0x19ab80c0
	s_mov_b64 s[42:43], 0x17e880c0
	s_mov_b64 s[44:45], 0x17e980c0
